# adds: attention QK K-fragment reads issued as a rolling 4-deep window into dead registers (v98-v129, v6-v17), counted lgkmcnt
# baseline (speedup 1.0000x reference)
.LBB0_120:
	s_bitcmp1_b32 s86, 0
	s_cselect_b32 s87, 0x4800, 0
	v_add3_u32 v2, s87, v183, v198
	ds_read_b128 v[98:101], v2 offset:4608
	ds_read_b128 v[102:105], v2
	ds_read_b128 v[106:109], v2 offset:32
	ds_read_b128 v[110:113], v2 offset:4672
	v_mov_b64_e32 v[80:81], v[64:65]
	v_mov_b64_e32 v[78:79], v[62:63]
	v_mov_b64_e32 v[76:77], v[60:61]
	v_mov_b64_e32 v[74:75], v[58:59]
	v_mov_b64_e32 v[72:73], v[56:57]
	v_mov_b64_e32 v[70:71], v[54:55]
	v_mov_b64_e32 v[68:69], v[52:53]
	v_mov_b64_e32 v[66:67], v[50:51]
	s_waitcnt lgkmcnt(2)
	v_mfma_f32_32x32x16_bf16 v[82:97], v[102:105], v[130:133], v[50:65]
	ds_read_b128 v[114:117], v2 offset:4640
	s_cmp_lt_u32 s86, 4
	s_cselect_b64 s[2:3], -1, 0
	s_or_b64 s[2:3], s[76:77], s[2:3]
	s_and_b64 vcc, exec, s[2:3]
	v_mfma_f32_32x32x16_bf16 v[66:81], v[98:101], v[130:133], v[66:81]
	ds_read_b128 v[118:121], v2 offset:64
	s_waitcnt lgkmcnt(3)
	v_mfma_f32_32x32x16_bf16 v[82:97], v[106:109], v[134:137], v[82:97]
	ds_read_b128 v[122:125], v2 offset:96
	s_waitcnt lgkmcnt(2)
	v_mfma_f32_32x32x16_bf16 v[66:81], v[114:117], v[134:137], v[66:81]
	ds_read_b128 v[126:129], v2 offset:4704
	s_waitcnt lgkmcnt(2)
	v_mfma_f32_32x32x16_bf16 v[82:97], v[118:121], v[138:141], v[82:97]
	v_mfma_f32_32x32x16_bf16 v[66:81], v[110:113], v[138:141], v[66:81]
	s_waitcnt lgkmcnt(1)
	v_mfma_f32_32x32x16_bf16 v[82:97], v[122:125], v[142:145], v[82:97]
	s_waitcnt lgkmcnt(0)
	v_mfma_f32_32x32x16_bf16 v[66:81], v[126:129], v[142:145], v[66:81]
	s_cbranch_vccnz .LBB0_190
	s_mov_b64 s[2:3], -1
	s_and_b64 vcc, exec, s[70:71]
	s_cbranch_vccz .LBB0_187
	s_add_i32 s2, s85, s86
	v_cmp_ge_i32_e32 vcc, s2, v178
	v_cmp_lt_i32_e64 s[2:3], s2, v180
	v_readlane_b32 s88, v254, 33
	s_and_b64 s[2:3], vcc, s[2:3]
	v_readlane_b32 s89, v254, 34
	s_and_b64 s[88:89], s[2:3], s[88:89]
	v_mov_b32_e32 v114, 0xf149f2ca
	v_mov_b32_e32 v98, 0xf149f2ca
	s_and_saveexec_b64 vcc, s[88:89]
	s_cbranch_execz .LBB0_124
	v_add_u32_e32 v2, v187, v186
	ds_read_b32 v2, v2 offset:37296
	s_waitcnt lgkmcnt(0)
	v_add_f32_e32 v98, v82, v2

.LBB0_214:
	s_bitcmp1_b32 s77, 0
	s_cselect_b32 s2, 0x5800, 0
	v_add3_u32 v2, s2, v217, v193
	ds_read_b128 v[98:101], v2 offset:6656
	ds_read_b128 v[102:105], v2
	ds_read_b128 v[106:109], v2 offset:32
	ds_read_b128 v[110:113], v2 offset:6720
	v_mov_b64_e32 v[80:81], v[64:65]
	v_mov_b64_e32 v[78:79], v[62:63]
	v_mov_b64_e32 v[76:77], v[60:61]
	v_mov_b64_e32 v[74:75], v[58:59]
	v_mov_b64_e32 v[72:73], v[56:57]
	v_mov_b64_e32 v[70:71], v[54:55]
	v_mov_b64_e32 v[68:69], v[52:53]
	v_mov_b64_e32 v[66:67], v[50:51]
	s_waitcnt lgkmcnt(2)
	v_mfma_f32_32x32x16_bf16 v[82:97], v[102:105], v[130:133], v[50:65]
	ds_read_b128 v[114:117], v2 offset:6688
	s_cmp_lt_u32 s77, 4
	s_cselect_b64 s[38:39], -1, 0
	s_xor_b64 vcc, s[68:69], -1
	s_or_b64 s[38:39], vcc, s[38:39]
	s_and_b64 vcc, exec, s[38:39]
	v_mfma_f32_32x32x16_bf16 v[66:81], v[98:101], v[130:133], v[66:81]
	ds_read_b128 v[118:121], v2 offset:64
	s_waitcnt lgkmcnt(3)
	v_mfma_f32_32x32x16_bf16 v[82:97], v[106:109], v[134:137], v[82:97]
	ds_read_b128 v[122:125], v2 offset:96
	s_waitcnt lgkmcnt(2)
	v_mfma_f32_32x32x16_bf16 v[66:81], v[114:117], v[134:137], v[66:81]
	ds_read_b128 v[126:129], v2 offset:6752
	s_waitcnt lgkmcnt(2)
	v_mfma_f32_32x32x16_bf16 v[82:97], v[118:121], v[138:141], v[82:97]
	ds_read_b128 v[6:9], v2 offset:128
	v_mfma_f32_32x32x16_bf16 v[66:81], v[110:113], v[138:141], v[66:81]
	ds_read_b128 v[10:13], v2 offset:6784
	s_waitcnt lgkmcnt(3)
	v_mfma_f32_32x32x16_bf16 v[82:97], v[122:125], v[142:145], v[82:97]
	ds_read_b128 v[14:17], v2 offset:160
	s_waitcnt lgkmcnt(3)
	v_mfma_f32_32x32x16_bf16 v[66:81], v[126:129], v[142:145], v[66:81]
	ds_read_b128 v[102:105], v2 offset:6816
	s_waitcnt lgkmcnt(3)
	v_mfma_f32_32x32x16_bf16 v[82:97], v[6:9], v[146:149], v[82:97]
	s_waitcnt lgkmcnt(2)
	v_mfma_f32_32x32x16_bf16 v[66:81], v[10:13], v[146:149], v[66:81]
	s_waitcnt lgkmcnt(1)
	v_mfma_f32_32x32x16_bf16 v[82:97], v[14:17], v[150:153], v[82:97]
	s_waitcnt lgkmcnt(0)
	v_mfma_f32_32x32x16_bf16 v[66:81], v[102:105], v[150:153], v[66:81]
	s_cbranch_vccnz .LBB0_284
	s_mov_b64 s[38:39], -1
	s_and_b64 vcc, exec, s[70:71]
	s_cbranch_vccz .LBB0_281
	s_add_i32 s3, s42, s77
	v_cmp_ge_i32_e64 s[38:39], s3, v213
	v_cmp_lt_i32_e32 vcc, s3, v215
	v_readlane_b32 s72, v254, 33
	s_and_b64 s[38:39], s[38:39], vcc
	v_readlane_b32 s73, v254, 34
	s_and_b64 s[72:73], s[38:39], s[72:73]
	v_mov_b32_e32 v114, 0xf149f2ca
	v_mov_b32_e32 v98, 0xf149f2ca
	s_and_saveexec_b64 vcc, s[72:73]
	s_cbranch_execz .LBB0_218
	v_add_u32_e32 v2, v221, v220
	ds_read_b32 v2, v2 offset:45488
	s_waitcnt lgkmcnt(0)
	v_add_f32_e32 v98, v82, v2
